# v51 + q|k rotary epilogue: second store of a row group deferred behind the next group's loads, vmcnt(1)
# baseline (speedup 1.0000x reference)
; DI unsigned pk2(float a, float b) { f32x2 v = {a, b}; hbf2 r = __builtin_convertvector(v, hbf2); return __builtin_bit_cast(unsigned, r); }
;     DI void operator()(const f32x4 (&acc)[2][2][4][2], const Unit& u, int wr, int wc, int fr, int fq) const {
;     ...
;             for (int m = 0; m < 4; ++m) {
;                 const int r = row0 + ai * 128 + m * 16;
;                 const float rstd = rsqrtf(ss[r] * (1.0f / 1024.0f) + EPS);
;                 const int t = r < MR ? 16 + (r & 4095) : ((r - MR) & 15);
;                 f32x4 cs[2], sn[2];
;                 if (rot) {
;                     cs[0] = *(const f32x4*)(rope + t * 16); cs[1] = *(const f32x4*)(rope + t * 16 + 4);
;                     sn[0] = *(const f32x4*)(rope + t * 16 + 8); sn[1] = *(const f32x4*)(rope + t * 16 + 12);
;                 }
;                 bf16_t* rowp = QK + (size_t)r * 2048 + col0;
; #pragma unroll
;                 for (int bj = 0; bj < 2; ++bj) {
;                     f32x4 v[2]; v[0] = acc[ai][bj][m][0] * rstd; v[1] = acc[ai][bj][m][1] * rstd;
;                     if (rot) {
; #pragma unroll
;                         for (int n = 0; n < 2; ++n)
; #pragma unroll
;                             for (int j = 0; j < 4; ++j) {
;                                 const auto sw = __builtin_amdgcn_permlane16_swap(__float_as_uint(v[n][j]), __float_as_uint(v[n][j]), false, false);
;                                 const float other = __uint_as_float((fq & 1) ? sw[0] : sw[1]);
;                                 const float mine = v[n][j];
;                                 const float ra = mine * cs[n][j] - other * sn[n][j];
;                                 const float rb = mine * cs[n][j] + other * sn[n][j];
;                                 v[n][j] = fq == 0 ? ra : (fq == 1 ? rb : mine);
;                             }
;                     }
;                     u32x4 w; w.x = pk2(v[0][0], v[0][1]); w.y = pk2(v[0][2], v[0][3]); w.z = pk2(v[1][0], v[1][1]); w.w = pk2(v[1][2], v[1][3]);
;                     *(u32x4*)(rowp + bj * 128) = w;
.LBB0_1125:
	v_cvt_pk_bf16_f32 v132, v132, v133
	v_cvt_pk_bf16_f32 v133, v134, v135
	v_cvt_pk_bf16_f32 v134, v128, v129
	v_or_b32_e32 v128, 16, v160
	v_cvt_pk_bf16_f32 v135, v130, v131
	v_ashrrev_i32_e32 v129, 31, v128
	s_nop 0
	v_lshl_add_u64 v[130:131], v[128:129], 2, s[44:45]
	global_load_dword v130, v[130:131], off
	s_and_b64 vcc, exec, s[14:15]
	s_cbranch_vccnz .LBB0_1127
	v_and_b32_e32 v32, 0xfdf, v128
	v_add_u32_e32 v32, 16, v32
	v_cmp_gt_i32_e32 vcc, s56, v128
	s_nop 1
	v_cndmask_b32_e32 v32, v170, v32, vcc
	v_lshlrev_b32_e32 v48, 6, v32
	global_load_dwordx4 v[32:35], v48, s[86:87] offset:48
	global_load_dwordx4 v[40:43], v48, s[86:87] offset:32
	global_load_dwordx4 v[36:39], v48, s[86:87] offset:16
	s_nop 0
	global_load_dwordx4 v[48:51], v48, s[86:87]
.LBB0_1127:
	global_store_dwordx4 v[168:169], v[132:135], off offset:256
	s_waitcnt vmcnt(1)
	v_fmamk_f32 v130, v130, 0x3a800000, v177
	v_mul_f32_e32 v131, 0x4b800000, v130
	v_cmp_gt_f32_e32 vcc, s63, v130
	s_mov_b64 s[30:31], -1
	s_nop 0
	v_cndmask_b32_e32 v130, v130, v131, vcc
	v_rsq_f32_e32 v130, v130
	s_nop 0
	v_mul_f32_e32 v131, 0x45800000, v130
	v_cndmask_b32_e32 v130, v130, v131, vcc
	v_pk_mul_f32 v[126:127], v[126:127], v[130:131] op_sel_hi:[1,0]
	v_pk_mul_f32 v[124:125], v[124:125], v[130:131] op_sel_hi:[1,0]
	v_pk_mul_f32 v[122:123], v[122:123], v[130:131] op_sel_hi:[1,0]
	v_pk_mul_f32 v[132:133], v[120:121], v[130:131] op_sel_hi:[1,0]
	s_and_b64 vcc, exec, s[12:13]
	s_cbranch_vccnz .LBB0_1129
	s_mov_b64 s[30:31], 0

; DI unsigned pk2(float a, float b) { f32x2 v = {a, b}; hbf2 r = __builtin_convertvector(v, hbf2); return __builtin_bit_cast(unsigned, r); }
;     DI void operator()(const f32x4 (&acc)[2][2][4][2], const Unit& u, int wr, int wc, int fr, int fq) const {
;     ...
;             for (int m = 0; m < 4; ++m) {
;                 const int r = row0 + ai * 128 + m * 16;
;                 const float rstd = rsqrtf(ss[r] * (1.0f / 1024.0f) + EPS);
;                 const int t = r < MR ? 16 + (r & 4095) : ((r - MR) & 15);
;                 f32x4 cs[2], sn[2];
;                 if (rot) {
;                     cs[0] = *(const f32x4*)(rope + t * 16); cs[1] = *(const f32x4*)(rope + t * 16 + 4);
;                     sn[0] = *(const f32x4*)(rope + t * 16 + 8); sn[1] = *(const f32x4*)(rope + t * 16 + 12);
;                 }
;                 bf16_t* rowp = QK + (size_t)r * 2048 + col0;
; #pragma unroll
;                 for (int bj = 0; bj < 2; ++bj) {
;                     f32x4 v[2]; v[0] = acc[ai][bj][m][0] * rstd; v[1] = acc[ai][bj][m][1] * rstd;
;                     if (rot) {
; #pragma unroll
;                         for (int n = 0; n < 2; ++n)
; #pragma unroll
;                             for (int j = 0; j < 4; ++j) {
;                                 const auto sw = __builtin_amdgcn_permlane16_swap(__float_as_uint(v[n][j]), __float_as_uint(v[n][j]), false, false);
;                                 const float other = __uint_as_float((fq & 1) ? sw[0] : sw[1]);
;                                 const float mine = v[n][j];
;                                 const float ra = mine * cs[n][j] - other * sn[n][j];
;                                 const float rb = mine * cs[n][j] + other * sn[n][j];
;                                 v[n][j] = fq == 0 ? ra : (fq == 1 ? rb : mine);
;                             }
;                     }
;                     u32x4 w; w.x = pk2(v[0][0], v[0][1]); w.y = pk2(v[0][2], v[0][3]); w.z = pk2(v[1][0], v[1][1]); w.w = pk2(v[1][2], v[1][3]);
;                     *(u32x4*)(rowp + bj * 128) = w;
.LBB0_1135:
	v_cvt_pk_bf16_f32 v116, v116, v117
	v_cvt_pk_bf16_f32 v117, v118, v119
	v_cvt_pk_bf16_f32 v118, v112, v113
	v_or_b32_e32 v112, 32, v160
	v_cvt_pk_bf16_f32 v119, v114, v115
	v_ashrrev_i32_e32 v113, 31, v112
	s_nop 0
	v_lshl_add_u64 v[114:115], v[112:113], 2, s[44:45]
	global_load_dword v114, v[114:115], off
	s_and_b64 vcc, exec, s[14:15]
	s_cbranch_vccnz .LBB0_1137
	v_and_or_b32 v32, v112, s70, 16
	v_cmp_gt_i32_e32 vcc, s56, v112
	s_nop 1
	v_cndmask_b32_e32 v32, v170, v32, vcc
	v_lshlrev_b32_e32 v48, 6, v32
	global_load_dwordx4 v[32:35], v48, s[86:87] offset:48
	global_load_dwordx4 v[40:43], v48, s[86:87] offset:32
	global_load_dwordx4 v[36:39], v48, s[86:87] offset:16
	s_nop 0
	global_load_dwordx4 v[48:51], v48, s[86:87]
.LBB0_1137:
	global_store_dwordx4 v[120:121], v[116:119], off offset:256
	s_waitcnt vmcnt(1)
	v_fmamk_f32 v114, v114, 0x3a800000, v177
	v_mul_f32_e32 v115, 0x4b800000, v114
	v_cmp_gt_f32_e32 vcc, s63, v114
	s_mov_b64 s[30:31], -1
	s_nop 0
	v_cndmask_b32_e32 v114, v114, v115, vcc
	v_rsq_f32_e32 v114, v114
	s_nop 0
	v_mul_f32_e32 v115, 0x45800000, v114
	v_cndmask_b32_e32 v114, v114, v115, vcc
	v_pk_mul_f32 v[110:111], v[110:111], v[114:115] op_sel_hi:[1,0]
	v_pk_mul_f32 v[108:109], v[108:109], v[114:115] op_sel_hi:[1,0]
	v_pk_mul_f32 v[106:107], v[106:107], v[114:115] op_sel_hi:[1,0]
	v_pk_mul_f32 v[116:117], v[104:105], v[114:115] op_sel_hi:[1,0]
	s_and_b64 vcc, exec, s[12:13]
	s_cbranch_vccnz .LBB0_1139
	s_mov_b64 s[30:31], 0

; DI unsigned pk2(float a, float b) { f32x2 v = {a, b}; hbf2 r = __builtin_convertvector(v, hbf2); return __builtin_bit_cast(unsigned, r); }
;     DI void operator()(const f32x4 (&acc)[2][2][4][2], const Unit& u, int wr, int wc, int fr, int fq) const {
;     ...
;             for (int m = 0; m < 4; ++m) {
;                 const int r = row0 + ai * 128 + m * 16;
;                 const float rstd = rsqrtf(ss[r] * (1.0f / 1024.0f) + EPS);
;                 const int t = r < MR ? 16 + (r & 4095) : ((r - MR) & 15);
;                 f32x4 cs[2], sn[2];
;                 if (rot) {
;                     cs[0] = *(const f32x4*)(rope + t * 16); cs[1] = *(const f32x4*)(rope + t * 16 + 4);
;                     sn[0] = *(const f32x4*)(rope + t * 16 + 8); sn[1] = *(const f32x4*)(rope + t * 16 + 12);
;                 }
;                 bf16_t* rowp = QK + (size_t)r * 2048 + col0;
; #pragma unroll
;                 for (int bj = 0; bj < 2; ++bj) {
;                     f32x4 v[2]; v[0] = acc[ai][bj][m][0] * rstd; v[1] = acc[ai][bj][m][1] * rstd;
;                     if (rot) {
; #pragma unroll
;                         for (int n = 0; n < 2; ++n)
; #pragma unroll
;                             for (int j = 0; j < 4; ++j) {
;                                 const auto sw = __builtin_amdgcn_permlane16_swap(__float_as_uint(v[n][j]), __float_as_uint(v[n][j]), false, false);
;                                 const float other = __uint_as_float((fq & 1) ? sw[0] : sw[1]);
;                                 const float mine = v[n][j];
;                                 const float ra = mine * cs[n][j] - other * sn[n][j];
;                                 const float rb = mine * cs[n][j] + other * sn[n][j];
;                                 v[n][j] = fq == 0 ? ra : (fq == 1 ? rb : mine);
;                             }
;                     }
;                     u32x4 w; w.x = pk2(v[0][0], v[0][1]); w.y = pk2(v[0][2], v[0][3]); w.z = pk2(v[1][0], v[1][1]); w.w = pk2(v[1][2], v[1][3]);
;                     *(u32x4*)(rowp + bj * 128) = w;
.LBB0_1145:
	v_cvt_pk_bf16_f32 v100, v100, v101
	v_cvt_pk_bf16_f32 v101, v102, v103
	v_cvt_pk_bf16_f32 v102, v96, v97
	v_or_b32_e32 v96, 48, v160
	v_cvt_pk_bf16_f32 v103, v98, v99
	v_ashrrev_i32_e32 v97, 31, v96
	s_nop 0
	v_lshl_add_u64 v[98:99], v[96:97], 2, s[44:45]
	global_load_dword v98, v[98:99], off
	s_and_b64 vcc, exec, s[14:15]
	s_cbranch_vccnz .LBB0_1147
	v_and_b32_e32 v32, 0xfff, v96
	v_add_u32_e32 v32, 16, v32
	v_cmp_gt_i32_e32 vcc, s56, v96
	s_nop 1
	v_cndmask_b32_e32 v32, v170, v32, vcc
	v_lshlrev_b32_e32 v48, 6, v32
	global_load_dwordx4 v[32:35], v48, s[86:87] offset:48
	global_load_dwordx4 v[40:43], v48, s[86:87] offset:32
	global_load_dwordx4 v[36:39], v48, s[86:87] offset:16
	s_nop 0
	global_load_dwordx4 v[48:51], v48, s[86:87]
.LBB0_1147:
	global_store_dwordx4 v[104:105], v[100:103], off offset:256
	s_waitcnt vmcnt(1)
	v_fmamk_f32 v98, v98, 0x3a800000, v177
	v_mul_f32_e32 v99, 0x4b800000, v98
	v_cmp_gt_f32_e32 vcc, s63, v98
	s_mov_b64 s[30:31], -1
	s_nop 0
	v_cndmask_b32_e32 v98, v98, v99, vcc
	v_rsq_f32_e32 v98, v98
	s_nop 0
	v_mul_f32_e32 v99, 0x45800000, v98
	v_cndmask_b32_e32 v98, v98, v99, vcc
	v_pk_mul_f32 v[94:95], v[94:95], v[98:99] op_sel_hi:[1,0]
	v_pk_mul_f32 v[92:93], v[92:93], v[98:99] op_sel_hi:[1,0]
	v_pk_mul_f32 v[90:91], v[90:91], v[98:99] op_sel_hi:[1,0]
	v_pk_mul_f32 v[100:101], v[88:89], v[98:99] op_sel_hi:[1,0]
	s_and_b64 vcc, exec, s[12:13]
	s_cbranch_vccnz .LBB0_1149
	s_mov_b64 s[30:31], 0

; DI unsigned pk2(float a, float b) { f32x2 v = {a, b}; hbf2 r = __builtin_convertvector(v, hbf2); return __builtin_bit_cast(unsigned, r); }
;     DI void operator()(const f32x4 (&acc)[2][2][4][2], const Unit& u, int wr, int wc, int fr, int fq) const {
;     ...
;             for (int m = 0; m < 4; ++m) {
;                 const int r = row0 + ai * 128 + m * 16;
;                 const float rstd = rsqrtf(ss[r] * (1.0f / 1024.0f) + EPS);
;                 const int t = r < MR ? 16 + (r & 4095) : ((r - MR) & 15);
;                 f32x4 cs[2], sn[2];
;                 if (rot) {
;                     cs[0] = *(const f32x4*)(rope + t * 16); cs[1] = *(const f32x4*)(rope + t * 16 + 4);
;                     sn[0] = *(const f32x4*)(rope + t * 16 + 8); sn[1] = *(const f32x4*)(rope + t * 16 + 12);
;                 }
;                 bf16_t* rowp = QK + (size_t)r * 2048 + col0;
; #pragma unroll
;                 for (int bj = 0; bj < 2; ++bj) {
;                     f32x4 v[2]; v[0] = acc[ai][bj][m][0] * rstd; v[1] = acc[ai][bj][m][1] * rstd;
;                     if (rot) {
; #pragma unroll
;                         for (int n = 0; n < 2; ++n)
; #pragma unroll
;                             for (int j = 0; j < 4; ++j) {
;                                 const auto sw = __builtin_amdgcn_permlane16_swap(__float_as_uint(v[n][j]), __float_as_uint(v[n][j]), false, false);
;                                 const float other = __uint_as_float((fq & 1) ? sw[0] : sw[1]);
;                                 const float mine = v[n][j];
;                                 const float ra = mine * cs[n][j] - other * sn[n][j];
;                                 const float rb = mine * cs[n][j] + other * sn[n][j];
;                                 v[n][j] = fq == 0 ? ra : (fq == 1 ? rb : mine);
;                             }
;                     }
;                     u32x4 w; w.x = pk2(v[0][0], v[0][1]); w.y = pk2(v[0][2], v[0][3]); w.z = pk2(v[1][0], v[1][1]); w.w = pk2(v[1][2], v[1][3]);
;                     *(u32x4*)(rowp + bj * 128) = w;
.LBB0_1155:
	v_cvt_pk_bf16_f32 v84, v84, v85
	v_cvt_pk_bf16_f32 v85, v86, v87
	v_cvt_pk_bf16_f32 v86, v80, v81
	v_cvt_pk_bf16_f32 v87, v82, v83
	s_nop 0
	global_load_dword v82, v[162:163], off offset:512
	v_add_u32_e32 v80, 0x80, v160
	s_and_b64 vcc, exec, s[14:15]
	v_ashrrev_i32_e32 v81, 31, v80
	s_cbranch_vccnz .LBB0_1157
	v_and_or_b32 v32, v80, s62, 16
	v_cmp_gt_i32_e32 vcc, s71, v160
	s_nop 1
	v_cndmask_b32_e32 v32, v170, v32, vcc
	v_lshlrev_b32_e32 v48, 6, v32
	global_load_dwordx4 v[32:35], v48, s[86:87] offset:48
	global_load_dwordx4 v[40:43], v48, s[86:87] offset:32
	global_load_dwordx4 v[36:39], v48, s[86:87] offset:16
	s_nop 0
	global_load_dwordx4 v[48:51], v48, s[86:87]
.LBB0_1157:
	global_store_dwordx4 v[88:89], v[84:87], off offset:256
	s_waitcnt vmcnt(1)
	v_fmamk_f32 v82, v82, 0x3a800000, v177
	v_mul_f32_e32 v83, 0x4b800000, v82
	v_cmp_gt_f32_e32 vcc, s63, v82
	s_mov_b64 s[30:31], -1
	s_nop 0
	v_cndmask_b32_e32 v82, v82, v83, vcc
	v_rsq_f32_e32 v82, v82
	s_nop 0
	v_mul_f32_e32 v83, 0x45800000, v82
	v_cndmask_b32_e32 v82, v82, v83, vcc
	v_pk_mul_f32 v[78:79], v[78:79], v[82:83] op_sel_hi:[1,0]
	v_pk_mul_f32 v[76:77], v[76:77], v[82:83] op_sel_hi:[1,0]
	v_pk_mul_f32 v[74:75], v[74:75], v[82:83] op_sel_hi:[1,0]
	v_pk_mul_f32 v[84:85], v[72:73], v[82:83] op_sel_hi:[1,0]
	s_and_b64 vcc, exec, s[12:13]
	s_cbranch_vccnz .LBB0_1159
	s_mov_b64 s[30:31], 0

; DI unsigned pk2(float a, float b) { f32x2 v = {a, b}; hbf2 r = __builtin_convertvector(v, hbf2); return __builtin_bit_cast(unsigned, r); }
;     DI void operator()(const f32x4 (&acc)[2][2][4][2], const Unit& u, int wr, int wc, int fr, int fq) const {
;     ...
;             for (int m = 0; m < 4; ++m) {
;                 const int r = row0 + ai * 128 + m * 16;
;                 const float rstd = rsqrtf(ss[r] * (1.0f / 1024.0f) + EPS);
;                 const int t = r < MR ? 16 + (r & 4095) : ((r - MR) & 15);
;                 f32x4 cs[2], sn[2];
;                 if (rot) {
;                     cs[0] = *(const f32x4*)(rope + t * 16); cs[1] = *(const f32x4*)(rope + t * 16 + 4);
;                     sn[0] = *(const f32x4*)(rope + t * 16 + 8); sn[1] = *(const f32x4*)(rope + t * 16 + 12);
;                 }
;                 bf16_t* rowp = QK + (size_t)r * 2048 + col0;
; #pragma unroll
;                 for (int bj = 0; bj < 2; ++bj) {
;                     f32x4 v[2]; v[0] = acc[ai][bj][m][0] * rstd; v[1] = acc[ai][bj][m][1] * rstd;
;                     if (rot) {
; #pragma unroll
;                         for (int n = 0; n < 2; ++n)
; #pragma unroll
;                             for (int j = 0; j < 4; ++j) {
;                                 const auto sw = __builtin_amdgcn_permlane16_swap(__float_as_uint(v[n][j]), __float_as_uint(v[n][j]), false, false);
;                                 const float other = __uint_as_float((fq & 1) ? sw[0] : sw[1]);
;                                 const float mine = v[n][j];
;                                 const float ra = mine * cs[n][j] - other * sn[n][j];
;                                 const float rb = mine * cs[n][j] + other * sn[n][j];
;                                 v[n][j] = fq == 0 ? ra : (fq == 1 ? rb : mine);
;                             }
;                     }
;                     u32x4 w; w.x = pk2(v[0][0], v[0][1]); w.y = pk2(v[0][2], v[0][3]); w.z = pk2(v[1][0], v[1][1]); w.w = pk2(v[1][2], v[1][3]);
;                     *(u32x4*)(rowp + bj * 128) = w;
.LBB0_1165:
	v_cvt_pk_bf16_f32 v68, v68, v69
	v_cvt_pk_bf16_f32 v69, v70, v71
	v_cvt_pk_bf16_f32 v70, v64, v65
	v_cvt_pk_bf16_f32 v71, v66, v67
	s_nop 0
	global_load_dword v66, v[162:163], off offset:576
	v_add_u32_e32 v64, 0x90, v160
	s_and_b64 vcc, exec, s[14:15]
	v_ashrrev_i32_e32 v65, 31, v64
	s_cbranch_vccnz .LBB0_1167
	v_and_b32_e32 v32, 0xfdf, v64
	v_add_u32_e32 v32, 16, v32
	v_cmp_gt_i32_e32 vcc, s72, v160
	s_nop 1
	v_cndmask_b32_e32 v32, v170, v32, vcc
	v_lshlrev_b32_e32 v48, 6, v32
	global_load_dwordx4 v[32:35], v48, s[86:87] offset:48
	global_load_dwordx4 v[40:43], v48, s[86:87] offset:32
	global_load_dwordx4 v[36:39], v48, s[86:87] offset:16
	s_nop 0
	global_load_dwordx4 v[48:51], v48, s[86:87]
.LBB0_1167:
	global_store_dwordx4 v[72:73], v[68:71], off offset:256
	s_waitcnt vmcnt(1)
	v_fmamk_f32 v66, v66, 0x3a800000, v177
	v_mul_f32_e32 v67, 0x4b800000, v66
	v_cmp_gt_f32_e32 vcc, s63, v66
	s_mov_b64 s[30:31], -1
	s_nop 0
	v_cndmask_b32_e32 v66, v66, v67, vcc
	v_rsq_f32_e32 v66, v66
	s_nop 0
	v_mul_f32_e32 v67, 0x45800000, v66
	v_cndmask_b32_e32 v66, v66, v67, vcc
	v_pk_mul_f32 v[62:63], v[62:63], v[66:67] op_sel_hi:[1,0]
	v_pk_mul_f32 v[60:61], v[60:61], v[66:67] op_sel_hi:[1,0]
	v_pk_mul_f32 v[58:59], v[58:59], v[66:67] op_sel_hi:[1,0]
	v_pk_mul_f32 v[68:69], v[56:57], v[66:67] op_sel_hi:[1,0]
	s_and_b64 vcc, exec, s[12:13]
	s_cbranch_vccnz .LBB0_1169
	s_mov_b64 s[30:31], 0

; DI unsigned pk2(float a, float b) { f32x2 v = {a, b}; hbf2 r = __builtin_convertvector(v, hbf2); return __builtin_bit_cast(unsigned, r); }
;     DI void operator()(const f32x4 (&acc)[2][2][4][2], const Unit& u, int wr, int wc, int fr, int fq) const {
;     ...
;                 const int r = row0 + ai * 128 + m * 16;
;                 const float rstd = rsqrtf(ss[r] * (1.0f / 1024.0f) + EPS);
;                 const int t = r < MR ? 16 + (r & 4095) : ((r - MR) & 15);
;                 f32x4 cs[2], sn[2];
;                 if (rot) {
;                     cs[0] = *(const f32x4*)(rope + t * 16); cs[1] = *(const f32x4*)(rope + t * 16 + 4);
;                     sn[0] = *(const f32x4*)(rope + t * 16 + 8); sn[1] = *(const f32x4*)(rope + t * 16 + 12);
;                 }
;                 bf16_t* rowp = QK + (size_t)r * 2048 + col0;
; #pragma unroll
;                 for (int bj = 0; bj < 2; ++bj) {
;                     f32x4 v[2]; v[0] = acc[ai][bj][m][0] * rstd; v[1] = acc[ai][bj][m][1] * rstd;
;                     if (rot) {
; #pragma unroll
;                         for (int n = 0; n < 2; ++n)
; #pragma unroll
;                             for (int j = 0; j < 4; ++j) {
;                                 const auto sw = __builtin_amdgcn_permlane16_swap(__float_as_uint(v[n][j]), __float_as_uint(v[n][j]), false, false);
;                                 const float other = __uint_as_float((fq & 1) ? sw[0] : sw[1]);
;                                 const float mine = v[n][j];
;                                 const float ra = mine * cs[n][j] - other * sn[n][j];
;                                 const float rb = mine * cs[n][j] + other * sn[n][j];
;                                 v[n][j] = fq == 0 ? ra : (fq == 1 ? rb : mine);
;                             }
;                     }
;                     u32x4 w; w.x = pk2(v[0][0], v[0][1]); w.y = pk2(v[0][2], v[0][3]); w.z = pk2(v[1][0], v[1][1]); w.w = pk2(v[1][2], v[1][3]);
;                     *(u32x4*)(rowp + bj * 128) = w;
.LBB0_1175:
	v_cvt_pk_bf16_f32 v52, v52, v53
	v_cvt_pk_bf16_f32 v53, v54, v55
	v_cvt_pk_bf16_f32 v54, v44, v45
	v_cvt_pk_bf16_f32 v55, v46, v47
	s_nop 0
	global_load_dword v46, v[162:163], off offset:640
	v_add_u32_e32 v44, 0xa0, v160
	s_and_b64 vcc, exec, s[14:15]
	v_ashrrev_i32_e32 v45, 31, v44
	s_cbranch_vccnz .LBB0_1177
	v_and_or_b32 v32, v44, s70, 16
	v_cmp_gt_i32_e32 vcc, s73, v160
	s_nop 1
	v_cndmask_b32_e32 v32, v170, v32, vcc
	v_lshlrev_b32_e32 v47, 6, v32
	global_load_dwordx4 v[32:35], v47, s[86:87] offset:48
	global_load_dwordx4 v[40:43], v47, s[86:87] offset:32
	global_load_dwordx4 v[36:39], v47, s[86:87] offset:16
	global_load_dwordx4 v[48:51], v47, s[86:87]
.LBB0_1177:
	global_store_dwordx4 v[56:57], v[52:55], off offset:256
	s_waitcnt vmcnt(1)
	v_fmamk_f32 v46, v46, 0x3a800000, v177
	v_mul_f32_e32 v47, 0x4b800000, v46
	v_cmp_gt_f32_e32 vcc, s63, v46
	s_mov_b64 s[30:31], -1
	s_nop 0
	v_cndmask_b32_e32 v46, v46, v47, vcc
	v_rsq_f32_e32 v46, v46
	s_nop 0
	v_mul_f32_e32 v47, 0x45800000, v46
	v_cndmask_b32_e32 v46, v46, v47, vcc
	v_pk_mul_f32 v[30:31], v[30:31], v[46:47] op_sel_hi:[1,0]
	v_pk_mul_f32 v[28:29], v[28:29], v[46:47] op_sel_hi:[1,0]
	v_pk_mul_f32 v[26:27], v[26:27], v[46:47] op_sel_hi:[1,0]
	v_pk_mul_f32 v[52:53], v[24:25], v[46:47] op_sel_hi:[1,0]
	s_and_b64 vcc, exec, s[12:13]
	s_cbranch_vccnz .LBB0_1179
	s_mov_b64 s[30:31], 0

; DI unsigned pk2(float a, float b) { f32x2 v = {a, b}; hbf2 r = __builtin_convertvector(v, hbf2); return __builtin_bit_cast(unsigned, r); }
;     DI void operator()(const f32x4 (&acc)[2][2][4][2], const Unit& u, int wr, int wc, int fr, int fq) const {
;     ...
;                 const int r = row0 + ai * 128 + m * 16;
;                 const float rstd = rsqrtf(ss[r] * (1.0f / 1024.0f) + EPS);
;                 const int t = r < MR ? 16 + (r & 4095) : ((r - MR) & 15);
;                 f32x4 cs[2], sn[2];
;                 if (rot) {
;                     cs[0] = *(const f32x4*)(rope + t * 16); cs[1] = *(const f32x4*)(rope + t * 16 + 4);
;                     sn[0] = *(const f32x4*)(rope + t * 16 + 8); sn[1] = *(const f32x4*)(rope + t * 16 + 12);
;                 }
;                 bf16_t* rowp = QK + (size_t)r * 2048 + col0;
; #pragma unroll
;                 for (int bj = 0; bj < 2; ++bj) {
;                     f32x4 v[2]; v[0] = acc[ai][bj][m][0] * rstd; v[1] = acc[ai][bj][m][1] * rstd;
;                     if (rot) {
; #pragma unroll
;                         for (int n = 0; n < 2; ++n)
; #pragma unroll
;                             for (int j = 0; j < 4; ++j) {
;                                 const auto sw = __builtin_amdgcn_permlane16_swap(__float_as_uint(v[n][j]), __float_as_uint(v[n][j]), false, false);
;                                 const float other = __uint_as_float((fq & 1) ? sw[0] : sw[1]);
;                                 const float mine = v[n][j];
;                                 const float ra = mine * cs[n][j] - other * sn[n][j];
;                                 const float rb = mine * cs[n][j] + other * sn[n][j];
;                                 v[n][j] = fq == 0 ? ra : (fq == 1 ? rb : mine);
;                             }
;                     }
;                     u32x4 w; w.x = pk2(v[0][0], v[0][1]); w.y = pk2(v[0][2], v[0][3]); w.z = pk2(v[1][0], v[1][1]); w.w = pk2(v[1][2], v[1][3]);
;                     *(u32x4*)(rowp + bj * 128) = w;
.LBB0_1185:
	v_cvt_pk_bf16_f32 v20, v20, v21
	v_cvt_pk_bf16_f32 v21, v22, v23
	v_cvt_pk_bf16_f32 v22, v16, v17
	v_cvt_pk_bf16_f32 v23, v18, v19
	s_nop 0
	global_load_dword v18, v[162:163], off offset:704
	v_add_u32_e32 v16, 0xb0, v160
	s_and_b64 vcc, exec, s[14:15]
	v_ashrrev_i32_e32 v17, 31, v16
	s_cbranch_vccnz .LBB0_1187
	v_and_b32_e32 v19, 0xfff, v16
	v_add_u32_e32 v19, 16, v19
	v_cmp_gt_i32_e32 vcc, s74, v160
	s_nop 1
	v_cndmask_b32_e32 v19, v170, v19, vcc
	v_lshlrev_b32_e32 v19, 6, v19
	global_load_dwordx4 v[32:35], v19, s[86:87] offset:48
	global_load_dwordx4 v[40:43], v19, s[86:87] offset:32
	global_load_dwordx4 v[36:39], v19, s[86:87] offset:16
	global_load_dwordx4 v[48:51], v19, s[86:87]
.LBB0_1187:
	global_store_dwordx4 v[24:25], v[20:23], off offset:256
	s_waitcnt vmcnt(1)
	v_fmamk_f32 v18, v18, 0x3a800000, v177
	v_mul_f32_e32 v19, 0x4b800000, v18
	v_cmp_gt_f32_e32 vcc, s63, v18
	s_mov_b64 s[14:15], -1
	s_nop 0
	v_cndmask_b32_e32 v18, v18, v19, vcc
	v_rsq_f32_e32 v18, v18
	s_nop 0
	v_mul_f32_e32 v19, 0x45800000, v18
	v_cndmask_b32_e32 v18, v18, v19, vcc
	v_pk_mul_f32 v[14:15], v[14:15], v[18:19] op_sel_hi:[1,0]
	v_pk_mul_f32 v[12:13], v[12:13], v[18:19] op_sel_hi:[1,0]
	v_pk_mul_f32 v[10:11], v[10:11], v[18:19] op_sel_hi:[1,0]
	v_pk_mul_f32 v[20:21], v[8:9], v[18:19] op_sel_hi:[1,0]
	s_and_b64 vcc, exec, s[12:13]
	s_cbranch_vccnz .LBB0_1189
	s_mov_b64 s[14:15], 0
